# ssm pass-3 per-task setup: the four C-operand load pairs (each followed by vmcnt(0)) are issued together behind counted waits (3 fewer serialized round trips per task)
# speedup vs baseline: 1.0069x; 1.0004x over previous
; __device__ __forceinline__ unsigned pk2(float lo, float hi) { const f32x2 v = {lo, hi}; const bf16x2_t b = __builtin_convertvector(v, bf16x2_t); return __builtin_bit_cast(unsigned, b); }
; template <int PASS> __device__ __forceinline__ void ssm_phase(int j, LAS unsigned char* lds, int lane, int wave) { KARGS;
;     ...
;             const float* cre = a.in[I_CRE] + ((size_t)(j * 128 + g) * 16 + fr) * 64 + 4 * fq; const float* cim = a.in[I_CIM] + ((size_t)(j * 128 + g) * 16 + fr) * 64 + 4 * fq;
; #pragma unroll
;             for (int ks = 0; ks < 4; ++ks) { const f32x4 vr = *(const f32x4*)(cre + 16 * ks), vi = *(const f32x4*)(cim + 16 * ks);
;                 u32x4 w; w.x = pk2(vr[0], -vi[0]); w.y = pk2(vr[1], -vi[1]); w.z = pk2(vr[2], -vi[2]); w.w = pk2(vr[3], -vi[3]); cf[ks] = __builtin_bit_cast(bf16x8, w); }
;             dd = a.in[I_SD][(size_t)j * D + 16 * g + fr] * gmix[16 * g + fr];
.LBB0_337:
	s_or_b64 exec, exec, s[10:11]
	s_load_dwordx4 s[48:51], s[56:57], 0x88
	s_load_dwordx2 s[10:11], s[56:57], 0x98
	s_lshl_b64 s[4:5], s[4:5], 12
	v_lshl_or_b32 v36, v70, 2, s4
	v_mov_b32_e32 v37, s5
	s_waitcnt lgkmcnt(0)
	v_lshl_add_u64 v[38:39], s[48:49], 0, v[36:37]
	v_mov_b32_e32 v83, v193
	v_lshl_add_u64 v[52:53], v[38:39], 0, v[82:83]
	v_lshl_add_u64 v[36:37], s[50:51], 0, v[36:37]
	v_lshl_add_u64 v[54:55], v[36:37], 0, v[82:83]
	global_load_dwordx4 v[36:39], v[52:53], off
	global_load_dwordx4 v[40:43], v[54:55], off
	global_load_dwordx4 v[126:129], v[52:53], off offset:64
	global_load_dwordx4 v[130:133], v[54:55], off offset:64
	global_load_dwordx4 v[134:137], v[52:53], off offset:128
	global_load_dwordx4 v[138:141], v[54:55], off offset:128
	global_load_dwordx4 v[142:145], v[52:53], off offset:192
	global_load_dwordx4 v[146:149], v[54:55], off offset:192
	s_lshl_b32 s13, s52, 4
	s_ashr_i32 s12, s14, 8
	s_add_u32 s10, s10, s42
	s_addc_u32 s11, s11, s43
	s_lshl_b32 s4, s13, 2
	s_add_u32 s10, s10, s4
	v_or_b32_e32 v86, s13, v62
	s_addc_u32 s11, s11, 0
	s_mov_b32 s5, s69
	s_add_i32 s37, s12, 0x80
	v_lshl_add_u64 v[88:89], v[74:75], 0, s[4:5]
	s_lshl_b32 s52, s68, 2
	s_waitcnt vmcnt(6)
	v_xor_b32_e32 v3, 0x80000000, v40
	v_cvt_pk_bf16_f32 v36, v36, v3
	v_xor_b32_e32 v3, 0x80000000, v41
	v_cvt_pk_bf16_f32 v37, v37, v3
	v_xor_b32_e32 v3, 0x80000000, v42
	v_cvt_pk_bf16_f32 v38, v38, v3
	v_xor_b32_e32 v3, 0x80000000, v43
	s_waitcnt vmcnt(4)
	v_mov_b64_e32 v[40:41], v[126:127]
	v_mov_b64_e32 v[42:43], v[128:129]
	v_mov_b64_e32 v[44:45], v[130:131]
	v_mov_b64_e32 v[46:47], v[132:133]
	v_cvt_pk_bf16_f32 v39, v39, v3
	v_xor_b32_e32 v3, 0x80000000, v44
	v_cvt_pk_bf16_f32 v40, v40, v3
	v_xor_b32_e32 v3, 0x80000000, v45
	v_cvt_pk_bf16_f32 v41, v41, v3
	v_xor_b32_e32 v3, 0x80000000, v46
	v_cvt_pk_bf16_f32 v42, v42, v3
	v_xor_b32_e32 v3, 0x80000000, v47
	s_waitcnt vmcnt(2)
	v_mov_b64_e32 v[44:45], v[134:135]
	v_mov_b64_e32 v[46:47], v[136:137]
	v_mov_b64_e32 v[48:49], v[138:139]
	v_mov_b64_e32 v[50:51], v[140:141]
	v_cvt_pk_bf16_f32 v43, v43, v3
	v_xor_b32_e32 v3, 0x80000000, v48
	v_cvt_pk_bf16_f32 v44, v44, v3
	v_xor_b32_e32 v3, 0x80000000, v49
	v_cvt_pk_bf16_f32 v45, v45, v3
	v_xor_b32_e32 v3, 0x80000000, v50
	v_cvt_pk_bf16_f32 v46, v46, v3
	v_xor_b32_e32 v3, 0x80000000, v51
	s_waitcnt vmcnt(0)
	v_mov_b64_e32 v[48:49], v[142:143]
	v_mov_b64_e32 v[50:51], v[144:145]
	v_mov_b64_e32 v[52:53], v[146:147]
	v_mov_b64_e32 v[54:55], v[148:149]
	v_cvt_pk_bf16_f32 v47, v47, v3
	v_xor_b32_e32 v3, 0x80000000, v52
	v_cvt_pk_bf16_f32 v48, v48, v3
	v_xor_b32_e32 v3, 0x80000000, v53
	v_cvt_pk_bf16_f32 v49, v49, v3
	v_xor_b32_e32 v3, 0x80000000, v54
	v_cvt_pk_bf16_f32 v50, v50, v3
	v_xor_b32_e32 v3, 0x80000000, v55
	v_lshlrev_b32_e32 v52, 2, v86
	v_cvt_pk_bf16_f32 v51, v51, v3
	global_load_dword v3, v79, s[10:11]
	s_add_i32 s10, s12, s44
	global_load_dword v52, v52, s[66:67]
	s_ashr_i32 s11, s10, 31
	s_lshl_b64 s[10:11], s[10:11], 13
	s_or_b32 s10, s10, s68
	v_mov_b32_e32 v53, s11
	s_waitcnt vmcnt(0)
	v_mul_f32_e32 v83, v3, v52
	v_or_b32_e32 v52, s10, v60
	v_mov_b32_e32 v3, v2
	v_lshlrev_b64 v[90:91], 2, v[52:53]
	s_branch .LBB0_339
